# w_out: row panels also dealt in reverse order (newest MIX rows first; row phase then reads the newest residual rows first)
# baseline (speedup 1.0000x reference)
; #define PG8_BAR __builtin_amdgcn_s_barrier()
; template <class EpiT, bool ALIGN_EPI>
; __device__ __forceinline__ void gemm_phase(LAS unsigned char* lds, const Gemm g, const StaticOrder& S, const EpiT& E, const int tid) {
;     const int wid = __builtin_amdgcn_readfirstlane(tid >> 6), lane = tid & 63, wr = wid >> 2, wc = wid & 3, fr = lane & 15, fq = lane >> 4;
;     const int K = g.K;
;     unsigned voffA[2], voffB[2];
; #pragma unroll
;     for (int i = 0; i < 2; ++i) { int R, C; stage_rc(tid * 16 + i * 8192, R, C); const int Rb = (R & ~31) + perm32(R & 31);
;         voffA[i] = (unsigned)(R * K + C) * 2u; voffB[i] = (unsigned)(Rb * K + C) * 2u; }
;     const size_t kstep = (size_t)(BK * 2);
;     const size_t hstep = (size_t)HALF * K * 2;
;     const size_t tstep = 2 * hstep;
;     const unsigned ldsw = (unsigned)wid * 1024u;
;     const int aoff = lds_byte(wr * 64 + fr, fq * 8), boff = lds_byte(wc * 32 + fr, fq * 8);
;     ...
;     Unit cur, nxt; int ui = 0;
;     if (!S.next(0, cur)) return;
;     f32x4 acc[2][2][4][2];
; #pragma unroll
;     for (int a = 0; a < 2; ++a)
; #pragma unroll
;         for (int b = 0; b < 2; ++b)
; #pragma unroll
;             for (int m = 0; m < 4; ++m)
; #pragma unroll
;                 for (int n = 0; n < 2; ++n) acc[a][b][m][n] = (f32x4){0.f, 0.f, 0.f, 0.f};
;     bf16x8 At[4][2], B0[2][2], B1[2][2];
;     const char* cA; const char* cB; PG8_PTRS(cur, cA, cB);
;     PG8_STAGE(PG8_SB(0, 0), cB, voffB); PG8_STAGE(PG8_SB(0, 1), cB + hstep, voffB); PG8_STAGE(PG8_SA(0, 0), cA, voffA); PG8_STAGE(PG8_SA(0, 1), cA + hstep, voffA);
;     if (wr == 1) PG8_BAR;
;     PG8_WAIT_V(2); PG8_BAR;
; __global__ void __launch_bounds__(NTHR) fwd_kernel(Params p) {
;     ...
;                 pg8::Gemm g{(const bf16_t*)(q.ws + WS_MIX), (const bf16_t*)(q.ws + WS_WOUT) + (size_t)l * DM * DM, DM, 1 << 30};
;                 pg8::StaticOrder S; S.init(ML / 256, 4, G, (int)blockIdx.x, last ? 0 : MC / 256);
;                 pg8::FuseArgs fa{}; fa.ws = q.ws; fa.modl = mod + (size_t)l * 9 * NMOD; fa.modn = fa.modl; fa.gpost = q.in[I_GPOSTMIX] + l * DM; fa.gpre = q.in[I_GPREMLP] + l * DM;
;                 fa.gate_off = 2 * DM; fa.sh_off = 3 * DM; fa.sc_off = 4 * DM; fa.cbank = l * 4; fa.write_xn = 1; fa.out_f32 = 0;
;                 pg8::Epi<1> E{XN, nullptr, q.out, fa};
;                 pg8::gemm_phase<pg8::Epi<1>, true>(lds, g, S, E, tid);
.LBB0_223:
	s_and_b64 vcc, exec, s[0:1]
	s_cbranch_vccz .LBB0_313
	s_cmp_gt_i32 s46, 0
	s_mov_b64 s[0:1], -1
	s_cbranch_scc0 .LBB0_311
	s_cmp_gt_i32 s46, 1
	s_cbranch_scc0 .LBB0_293
	v_readlane_b32 s0, v255, 19
	v_readlane_b32 s1, v255, 20
	s_and_b64 s[0:1], s[0:1], exec
	s_movk_i32 s0, 0x300
	s_cselect_b32 s12, s0, 0x200
	s_cmp_ge_i32 s2, s12
	s_cselect_b64 s[0:1], -1, 0
	v_readfirstlane_b32 s10, v166
	s_and_b64 vcc, exec, s[0:1]
	s_cbranch_vccnz .LBB0_292
	s_waitcnt vmcnt(0)
	v_lshlrev_b32_e32 v0, 4, v166
	v_add_u32_e32 v1, 0x2000, v0
	v_readlane_b32 s4, v255, 17
	v_ashrrev_i32_e32 v2, 31, v1
	s_add_u32 s36, s73, 0x13200000
	v_readlane_b32 s5, v255, 18
	v_lshrrev_b32_e32 v2, 22, v2
	s_addc_u32 s37, s57, 0
	s_mov_b32 s6, s4
	s_ashr_i32 s7, s4, 31
	v_writelane_b32 v255, s4, 17
	v_add_u32_e32 v2, v1, v2
	v_ashrrev_i32_e32 v8, 10, v2
	v_writelane_b32 v255, s5, 18
	s_lshl_b64 s[4:5], s[6:7], 21
	s_add_u32 s4, s73, s4
	v_mul_i32_i24_e32 v2, 0x400, v8
	s_addc_u32 s5, s57, s5
	v_sub_u32_e32 v1, v1, v2
	s_add_u32 s39, s4, 0x1c00000
	v_lshrrev_b32_e32 v2, 4, v1
	s_addc_u32 s40, s5, 0
	v_readlane_b32 s4, v254, 4
	v_bitop3_b32 v1, v2, v1, 32 bitop3:0x6c
	s_ashr_i32 s6, s10, 6
	v_readlane_b32 s5, v254, 5
	v_ashrrev_i32_e32 v2, 31, v1
	s_ashr_i32 s7, s10, 8
	s_lshl_b32 s65, s6, 10
	s_or_b64 s[0:1], s[0:1], s[4:5]
	v_lshrrev_b32_e32 v2, 26, v2
	s_and_b64 s[0:1], s[0:1], exec
	v_add_u32_e32 v2, v1, v2
	v_lshlrev_b32_e32 v3, 3, v8
	v_readlane_b32 s0, v253, 11
	v_ashrrev_i32_e32 v9, 6, v2
	v_and_b32_e32 v3, -16, v3
	s_cselect_b32 s14, s0, -1
	v_readlane_b32 s0, v253, 12
	v_readlane_b32 s1, v253, 56
	v_add_u32_e32 v3, v9, v3
	s_cselect_b32 s16, s0, s1
	v_and_b32_e32 v4, 3, v9
	s_mov_b32 s0, 0x1fffe0
	v_lshrrev_b32_e32 v5, 2, v3
	v_lshlrev_b32_e32 v6, 1, v3
	v_and_b32_e32 v2, 0xc0, v2
	v_and_or_b32 v4, v3, s0, v4
	v_and_b32_e32 v5, 4, v5
	v_and_b32_e32 v6, 24, v6
	v_sub_u32_e32 v1, v1, v2
	v_or3_b32 v4, v4, v5, v6
	v_lshlrev_b32_e32 v5, 5, v8
	v_ashrrev_i16_sdwa v1, v252, sext(v1) dst_sel:DWORD dst_unused:UNUSED_PAD src0_sel:DWORD src1_sel:BYTE_0
	v_and_b32_e32 v5, 32, v5
	v_bfe_i32 v10, v1, 0, 16
	v_add_lshl_u32 v1, v5, v10, 1
	v_lshl_add_u32 v128, v4, 11, v1
	v_lshl_add_u32 v130, v3, 11, v1
	v_bfe_i32 v1, v166, 27, 1
	v_lshrrev_b32_e32 v1, 22, v1
	v_add_u32_e32 v1, v0, v1
	v_and_b32_e32 v1, 0xfffffc00, v1
	v_sub_u32_e32 v0, v0, v1
	v_lshrrev_b32_e32 v1, 4, v0
	v_ashrrev_i32_e32 v2, 31, v166
	v_bitop3_b32 v0, v1, v0, 32 bitop3:0x6c
	v_lshrrev_b32_e32 v2, 26, v2
	v_ashrrev_i32_e32 v1, 31, v0
	v_add_u32_e32 v2, v166, v2
	v_lshrrev_b32_e32 v1, 26, v1
	v_ashrrev_i32_e32 v12, 6, v2
	v_add_u32_e32 v1, v0, v1
	v_lshlrev_b32_e32 v2, 3, v12
	v_ashrrev_i32_e32 v11, 6, v1
	v_and_b32_e32 v2, -16, v2
	v_add_u32_e32 v2, v11, v2
	v_and_b32_e32 v3, 3, v11
	s_mov_b32 s15, s31
	v_and_or_b32 v3, v2, s0, v3
	s_lshl_b64 s[0:1], s[14:15], 8
	v_readlane_b32 s62, v254, 6
	s_and_b64 s[4:5], s[4:5], exec
	v_readlane_b32 s63, v254, 7
	s_cselect_b32 s4, s1, 0
	s_cselect_b32 s5, s0, 0
	s_ashr_i32 s63, s62, 31
	s_sub_i32 s0, 0x7f, s62
	s_mov_b32 s1, 0
	s_lshl_b64 s[0:1], s[0:1], 19
	s_add_u32 s0, s36, s0
	s_addc_u32 s1, s37, s1
	s_add_u32 s86, s0, s5
	s_addc_u32 s87, s1, s4
	s_ashr_i32 s17, s16, 31
	v_lshrrev_b32_e32 v4, 2, v2
	v_lshlrev_b32_e32 v5, 1, v2
	v_and_b32_e32 v1, 0xc0, v1
	s_lshl_b64 s[0:1], s[16:17], 19
	v_and_b32_e32 v4, 4, v4
	v_and_b32_e32 v5, 24, v5
	v_sub_u32_e32 v0, v0, v1
	s_add_u32 s0, s39, s0
	v_or3_b32 v3, v3, v4, v5
	v_lshlrev_b32_e32 v4, 5, v12
	v_ashrrev_i16_sdwa v0, v252, sext(v0) dst_sel:DWORD dst_unused:UNUSED_PAD src0_sel:DWORD src1_sel:BYTE_0
	s_addc_u32 s1, s40, s1
	v_and_b32_e32 v4, 32, v4
	v_bfe_i32 v13, v0, 0, 16
	s_add_u32 s68, s0, s5
	v_add_lshl_u32 v0, v4, v13, 1
	s_addc_u32 s69, s1, s4
	s_add_i32 s24, s65, 0
	v_lshl_add_u32 v156, v3, 11, v0
	s_add_i32 m0, s24, 0x10000
	v_lshl_add_u32 v132, v2, 11, v0
	global_load_lds_dwordx4 v156, s[68:69]
	s_add_i32 m0, s24, 0x12000
	s_add_u32 s0, s68, 0x40000
	global_load_lds_dwordx4 v128, s[68:69]
	s_addc_u32 s1, s69, 0
	s_add_i32 m0, s24, 0x14000
	s_add_i32 s25, s24, 0x2000
	global_load_lds_dwordx4 v156, s[0:1]
	s_add_i32 m0, s24, 0x16000
	v_mov_b32_e32 v129, v157
	global_load_lds_dwordx4 v128, s[0:1]
	s_mov_b32 m0, s24
	s_add_u32 s0, s86, 0x40000
	global_load_lds_dwordx4 v132, s[86:87]
	s_mov_b32 m0, s25
	s_addc_u32 s1, s87, 0
	s_add_i32 s33, s24, 0x4000
	global_load_lds_dwordx4 v130, s[86:87]
	s_mov_b32 m0, s33
	s_add_i32 s18, s24, 0x6000
	global_load_lds_dwordx4 v132, s[0:1]
	s_mov_b32 m0, s18
	v_mov_b32_e32 v133, v157
	global_load_lds_dwordx4 v130, s[0:1]
	v_mov_b32_e32 v131, v157
	s_cmp_eq_u32 s7, 1
	v_lshl_add_u64 v[6:7], s[68:69], 0, v[156:157]
	v_lshl_add_u64 v[4:5], s[68:69], 0, v[128:129]
	v_lshl_add_u64 v[0:1], s[86:87], 0, v[132:133]
	s_cselect_b64 s[44:45], -1, 0
	s_cmp_lg_u32 s7, 1
	v_lshl_add_u64 v[2:3], s[86:87], 0, v[130:131]
	s_cbranch_scc1 .LBB0_229
	s_barrier
; #define LAS __attribute__((address_space(3)))
; #define PG8_STAGE(bufoff, gbase, voff) do { _Pragma("unroll") for (int _i = 0; _i < 2; ++_i) \
;         __builtin_amdgcn_global_load_lds((const unsigned*)((const char*)(gbase) + (voff)[_i]), (LAS unsigned*)(lds + (bufoff) + ldsw + _i * 8192), 16, 0, 0); } while (0)
; #define PG8_WAIT_V(n) asm volatile("s_waitcnt vmcnt(" #n ")" ::: "memory")
; #define PG8_BAR __builtin_amdgcn_s_barrier()
; __device__ __forceinline__ void fused_epi(f32x4 (&acc)[2][2][4][2], const Unit& u, int wr, int wc, int fr, int fq, LAS unsigned char* xl, int wid, int lane, const FuseArgs& f) {
;     const int pm = u.pm, pn = u.pn; const size_t mrow = (size_t)(pm >> 4) * NMOD;
;     const int colb = pn * BM + wc * 32 + 8 * fq;
;     const LAS float* S = (const LAS float*)(xl + 4096);
;     panel_rms(acc, pm, pn, wr, wc, fr, fq, xl, wid, lane, (float*)(f.ws + WS_SLOT1), (unsigned*)(f.ws + WS_CNT) + f.cbank * CNT_BANK);
;     {
;         f32x4 Gv[2][2];
; #pragma unroll
;         for (int bj = 0; bj < 2; ++bj)
; #pragma unroll
;             for (int n = 0; n < 2; ++n) { const int c = colb + bj * HALF + 4 * n; Gv[bj][n] = *(const f32x4*)(f.modl + f.gate_off + mrow + c) * *(const f32x4*)(f.gpost + c); }
; #pragma unroll
;         for (int ai = 0; ai < 2; ++ai)
; #pragma unroll
;             for (int m = 0; m < 4; ++m) { const int r = ai * HALF + wr * 64 + m * 16 + fr; const float rstd = S[r];
; template <class EpiT, bool ALIGN_EPI>
; __device__ __forceinline__ void gemm_phase(LAS unsigned char* lds, const Gemm g, const StaticOrder& S, const EpiT& E, const int tid) {
;     ...
;     PG8_STAGE(PG8_SB(0, 0), cB, voffB); PG8_STAGE(PG8_SB(0, 1), cB + hstep, voffB); PG8_STAGE(PG8_SA(0, 0), cA, voffA); PG8_STAGE(PG8_SA(0, 1), cA + hstep, voffA);
;     if (wr == 1) PG8_BAR;
;     PG8_WAIT_V(2); PG8_BAR;
;     PG8_STAGE(PG8_SB(1, 0), cB + kstep, voffB); PG8_STAGE(PG8_SA(1, 0), cA + kstep, voffA); PG8_STAGE(PG8_SB(1, 1), cB + hstep + kstep, voffB);
;     PG8_WAIT_V(6); PG8_BAR;
.LBB0_229:
	v_readlane_b32 s0, v255, 17
	v_readlane_b32 s1, v255, 18
	s_mov_b32 s4, s0
	s_mul_i32 s1, s4, 0x36000
	s_mul_hi_i32 s0, s0, 0x36000
	s_add_u32 s11, s73, s1
	s_addc_u32 s15, s57, s0
	s_lshl_b32 s0, s4, 10
	s_ashr_i32 s1, s0, 31
	s_lshl_b64 s[0:1], s[0:1], 2
	v_readlane_b32 s5, v255, 21
	s_add_u32 s20, s5, s0
	v_readlane_b32 s0, v255, 23
	s_addc_u32 s21, s0, s1
	s_and_b32 s17, s6, 3
	s_add_i32 m0, s24, 0x18000
	v_lshl_add_u64 v[6:7], v[6:7], 0, s[88:89]
	s_lshl_b32 s0, s4, 15
	s_lshl_b32 s1, s7, 13
	s_lshl_b32 s9, s17, 12
	s_waitcnt vmcnt(2)
	s_barrier
	global_load_lds_dwordx4 v[6:7], off
	v_lshl_add_u64 v[4:5], v[4:5], 0, s[88:89]
	s_add_i32 m0, s24, 0x1a000
	s_add_i32 s19, s24, 0x8000
	s_add_i32 s8, s24, 0xa000
	global_load_lds_dwordx4 v[4:5], off
	v_lshl_add_u64 v[0:1], v[0:1], 0, s[88:89]
	s_mov_b32 m0, s19
	s_add_u32 s4, s68, 0x40080
	global_load_lds_dwordx4 v[0:1], off
	v_lshl_add_u64 v[0:1], v[2:3], 0, s[88:89]
	s_mov_b32 m0, s8
	s_addc_u32 s5, s69, 0
	global_load_lds_dwordx4 v[0:1], off
	s_add_i32 m0, s24, 0x1c000
	v_lshl_add_u64 v[0:1], s[4:5], 0, v[156:157]
	global_load_lds_dwordx4 v[0:1], off
	v_lshl_add_u64 v[0:1], s[4:5], 0, v[128:129]
	s_add_i32 m0, s24, 0x1e000
	v_and_b32_e32 v2, 48, v166
	global_load_lds_dwordx4 v[0:1], off
	v_and_b32_e32 v0, 15, v166
	v_lshl_or_b32 v167, s7, 6, v0
	v_lshlrev_b32_e32 v3, 2, v167
	v_and_b32_e32 v4, 32, v3
	v_lshl_or_b32 v2, v0, 6, v2
	s_cmpk_lt_u32 s10, 0x100
	v_bitop3_b32 v4, v2, s1, v4 bitop3:0xde
	s_cselect_b64 s[22:23], -1, 0
	s_lshl_b32 s1, s17, 2
	s_add_i32 s1, s1, 0
	s_lshl_b32 s7, s7, 10
	s_add_i32 s1, s1, s7
	s_add_i32 s26, s1, 0x20000
	v_lshrrev_b32_e32 v1, 1, v166
	v_lshlrev_b32_e32 v5, 2, v166
	s_cmp_lt_u32 s10, 64
	v_and_b32_e32 v1, 24, v1
	v_and_b32_e32 v5, 32, v5
	s_cselect_b64 s[28:29], -1, 0
	v_bitop3_b32 v172, s9, v2, v5 bitop3:0xf6
	v_and_b32_e32 v2, 31, v166
	v_writelane_b32 v255, s28, 21
	v_lshl_or_b32 v191, s17, 5, v1
	v_lshlrev_b32_e32 v1, 14, v12
	v_lshl_or_b32 v173, s6, 5, v2
	v_writelane_b32 v255, s29, 22
	v_readlane_b32 s1, v254, 28
	v_or_b32_e32 v176, 16, v167
	v_or_b32_e32 v178, 32, v167
	v_or_b32_e32 v180, 48, v167
	v_add_u32_e32 v182, 0x80, v167
	v_add_u32_e32 v184, 0x90, v167
	v_add_u32_e32 v186, 0xa0, v167
	v_add_u32_e32 v188, 0xb0, v167
	s_add_u32 s28, s73, 0x180000
	v_and_b32_e32 v1, 0xffff8000, v1
	v_lshl_add_u32 v174, v173, 2, s1
	v_add_u32_e32 v175, s1, v3
	v_lshl_add_u32 v177, v176, 2, s1
	v_lshl_add_u32 v179, v178, 2, s1
	v_lshl_add_u32 v181, v180, 2, s1
	v_lshl_add_u32 v183, v182, 2, s1
	v_lshl_add_u32 v185, v184, 2, s1
	v_lshl_add_u32 v187, v186, 2, s1
	v_lshl_add_u32 v189, v188, 2, s1
	s_addc_u32 s29, s57, 0
	s_ashr_i32 s1, s0, 31
	v_lshl_add_u32 v1, v11, 11, v1
	v_and_b32_e32 v3, 1, v12
	s_lshl_b64 s[0:1], s[0:1], 2
	v_lshl_or_b32 v1, v3, 6, v1
	s_add_u32 s0, s73, s0
	v_lshl_add_u32 v134, v13, 1, v1
	v_lshlrev_b32_e32 v1, 14, v8
	s_addc_u32 s1, s57, s1
	v_and_b32_e32 v1, 0xffff8000, v1
	s_add_u32 s41, s0, 0x100000
	v_lshl_add_u32 v1, v9, 11, v1
	v_and_b32_e32 v3, 1, v8
	s_waitcnt vmcnt(6)
	v_lshlrev_b32_e32 v2, 4, v173
	s_addc_u32 s47, s1, 0
	v_lshl_or_b32 v1, v3, 6, v1
	s_mov_b32 s0, s62
	v_lshlrev_b32_e32 v0, 4, v0
	s_add_u32 s56, s11, 0x2000
	v_lshl_add_u32 v136, v10, 1, v1
	v_add_u32_e32 v1, 0, v2
	v_writelane_b32 v254, s0, 6
	v_cmp_gt_u32_e64 s[4:5], 16, v168
	v_cmp_gt_u32_e64 s[6:7], 32, v168
	s_mov_b32 s9, 0
	v_cmp_eq_u32_e64 s[50:51], 0, v168
	v_add_u32_e32 v190, 0xffff8000, v167
	s_mov_b32 s13, s31
	s_addc_u32 s96, s15, 0
	v_mov_b32_e32 v135, v157
	v_mov_b32_e32 v137, v157
	v_add_u32_e32 v192, 0, v4
	v_add_u32_e32 v193, 0x20000, v1
	v_add_u32_e32 v194, s26, v0
	v_writelane_b32 v254, s1, 7
	s_sub_i32 s53, 0x7f, s62
	s_barrier
	s_branch .LBB0_232

; #define PG8_PTRS(u, pa, pb) do { const size_t _ko = (u).ks >= 0 ? (size_t)(u).ks * (size_t)(K / KSPLIT) * 2 : 0; \
;         const char* _a = (const char*)g.A + (size_t)(u).pm * tstep + _ko; const char* _b = (const char*)g.Bt + (size_t)(u).pn * tstep + _ko; \
;         if ((u).pn >= g.nN_main) { pa = _b; pb = _a; } else { pa = _a; pb = _b; } } while (0)
;     __device__ __forceinline__ bool next(int i, Unit& u) const {
;         const long L = (long)i * G + c; if (L >= nwg + nsplit * nN * KSPLIT) return false;
;         int pm, pn, ks;
;         if (L >= nwg) { const int e = (int)L - nwg, cu = e / KSPLIT; ks = e % KSPLIT; pm = nM + cu / nN; pn = cu % nN; }
;         else {
;             int wgid = (int)L; { const int q = nwg / NXCD, r = nwg % NXCD, xcd = wgid % NXCD, off = wgid / NXCD; wgid = (xcd < r ? xcd * (q + 1) : r * (q + 1) + (xcd - r) * q) + off; }
;             const int nig = WGM * nN, gid = wgid / nig, fm = gid * WGM, gsz = (nM - fm) < WGM ? (nM - fm) : WGM;
;             pm = fm + ((wgid % nig) % gsz); pn = (wgid % nig) / gsz; ks = -1;
;         }
;         u.pm = pm; u.pn = pn; u.ks = ks; return true;
; template <class EpiT, bool ALIGN_EPI>
; __device__ __forceinline__ void gemm_phase(LAS unsigned char* lds, const Gemm g, const StaticOrder& S, const EpiT& E, const int tid) {
;     ...
;         const bool has_next = S.next(ui + 1, nxt);
;         const char* nA = cA; const char* nB = cB; if (has_next) PG8_PTRS(nxt, nA, nB);
.LBB0_241:
	s_cmp_lt_i32 s30, 0
	s_cbranch_scc0 .Lrev_skip_241
	s_sub_i32 s76, 0x7f, s76
